# row phases de-serialised: split-K slab sums load all 8 slabs per piece together; final RMSNorm loads its 8 gain chunks together instead of one per store step behind vmcnt(0)
# speedup vs baseline: 1.0538x; 1.0109x over previous
.LBB0_945:
	s_or_b64 exec, exec, s[18:19]
	s_waitcnt vmcnt(0)
	v_pk_mul_f32 v[64:65], v[6:7], v[6:7]
	v_pk_mul_f32 v[68:69], v[10:11], v[10:11]
	v_pk_mul_f32 v[66:67], v[8:9], v[8:9]
	v_pk_mul_f32 v[70:71], v[12:13], v[12:13]
	v_add_f32_e32 v0, v69, v68
	v_add_f32_e32 v61, v65, v64
	v_add_f32_e32 v0, v70, v0
	v_add_f32_e32 v61, v66, v61
	v_pk_mul_f32 v[72:73], v[14:15], v[14:15]
	v_add_f32_e32 v0, v71, v0
	v_add_f32_e32 v61, v67, v61
	v_pk_mul_f32 v[74:75], v[16:17], v[16:17]
	v_add_f32_e32 v0, v61, v0
	v_add_f32_e32 v61, v73, v72
	v_add_f32_e32 v61, v74, v61
	v_pk_mul_f32 v[76:77], v[18:19], v[18:19]
	v_add_f32_e32 v61, v75, v61
	v_pk_mul_f32 v[78:79], v[20:21], v[20:21]
	v_add_f32_e32 v0, v0, v61
	v_add_f32_e32 v61, v77, v76
	v_add_f32_e32 v61, v78, v61
	v_pk_mul_f32 v[80:81], v[22:23], v[22:23]
	v_add_f32_e32 v61, v79, v61
	global_load_dwordx4 v[64:67], v[2:3], off
	global_load_dwordx4 v[154:157], v[2:3], off offset:1024
	global_load_dwordx4 v[158:161], v[2:3], off offset:2048
	global_load_dwordx4 v[162:165], v[2:3], off offset:3072
	global_load_dwordx4 v[170:173], v[50:51], off
	global_load_dwordx4 v[174:177], v[52:53], off
	global_load_dwordx4 v[182:185], v[54:55], off
	global_load_dwordx4 v[186:189], v[56:57], off
	v_pk_mul_f32 v[82:83], v[24:25], v[24:25]
	v_add_f32_e32 v0, v0, v61
	v_add_f32_e32 v61, v81, v80
	v_add_f32_e32 v61, v82, v61
	v_pk_mul_f32 v[84:85], v[26:27], v[26:27]
	v_add_f32_e32 v61, v83, v61
	v_pk_mul_f32 v[86:87], v[28:29], v[28:29]
	v_add_f32_e32 v0, v0, v61
	v_add_f32_e32 v61, v85, v84
	v_add_f32_e32 v61, v86, v61
	v_pk_mul_f32 v[88:89], v[30:31], v[30:31]
	v_add_f32_e32 v61, v87, v61
	v_pk_mul_f32 v[90:91], v[32:33], v[32:33]
	v_add_f32_e32 v0, v0, v61
	v_add_f32_e32 v61, v89, v88
	v_add_f32_e32 v61, v90, v61
	v_pk_mul_f32 v[92:93], v[34:35], v[34:35]
	v_add_f32_e32 v61, v91, v61
	v_pk_mul_f32 v[94:95], v[36:37], v[36:37]
	v_add_f32_e32 v0, v0, v61
	v_add_f32_e32 v61, v93, v92
	v_add_f32_e32 v61, v94, v61
	v_add_f32_e32 v61, v95, v61
	v_add_f32_e32 v0, v0, v61
	v_and_b32_e32 v61, 64, v205
	v_add_u32_e32 v61, 64, v61
	v_xor_b32_e32 v63, 32, v205
	v_cmp_lt_i32_e32 vcc, v63, v61
	s_movk_i32 s1, 0x1000
	s_nop 0
	v_cndmask_b32_e32 v63, v205, v63, vcc
	v_lshlrev_b32_e32 v63, 2, v63
	ds_bpermute_b32 v63, v63, v0
	s_waitcnt lgkmcnt(0)
	v_add_f32_e32 v0, v0, v63
	v_xor_b32_e32 v63, 16, v205
	v_cmp_lt_i32_e32 vcc, v63, v61
	s_nop 1
	v_cndmask_b32_e32 v63, v205, v63, vcc
	v_lshlrev_b32_e32 v63, 2, v63
	ds_bpermute_b32 v63, v63, v0
	s_waitcnt lgkmcnt(0)
	v_add_f32_e32 v0, v0, v63
	v_xor_b32_e32 v63, 8, v205
	v_cmp_lt_i32_e32 vcc, v63, v61
	s_nop 1
	v_cndmask_b32_e32 v63, v205, v63, vcc
	v_lshlrev_b32_e32 v63, 2, v63
	ds_bpermute_b32 v63, v63, v0
	s_waitcnt lgkmcnt(0)
	v_add_f32_e32 v0, v0, v63
	v_xor_b32_e32 v63, 4, v205
	v_cmp_lt_i32_e32 vcc, v63, v61
	s_nop 1
	v_cndmask_b32_e32 v63, v205, v63, vcc
	v_lshlrev_b32_e32 v63, 2, v63
	ds_bpermute_b32 v63, v63, v0
	s_waitcnt lgkmcnt(0)
	v_add_f32_e32 v0, v0, v63
	v_xor_b32_e32 v63, 2, v205
	v_cmp_lt_i32_e32 vcc, v63, v61
	s_nop 1
	v_cndmask_b32_e32 v63, v205, v63, vcc
	v_lshlrev_b32_e32 v63, 2, v63
	ds_bpermute_b32 v63, v63, v0
	s_waitcnt lgkmcnt(0)
	v_add_f32_e32 v0, v0, v63
	v_xor_b32_e32 v63, 1, v205
	v_cmp_lt_i32_e32 vcc, v63, v61
	s_nop 1
	v_cndmask_b32_e32 v61, v205, v63, vcc
	v_lshlrev_b32_e32 v61, 2, v61
	ds_bpermute_b32 v61, v61, v0
	v_ashrrev_i32_e32 v63, 31, v62
	v_lshlrev_b64 v[62:63], 24, v[62:63]
	v_lshl_add_u64 v[62:63], v[4:5], 0, v[62:63]
	s_waitcnt lgkmcnt(0)
	v_add_f32_e32 v0, v0, v61
	v_fmamk_f32 v0, v0, 0x3a000000, v180
	v_mul_f32_e32 v61, 0x4b800000, v0
	v_cmp_gt_f32_e32 vcc, s7, v0
	s_nop 1
	v_cndmask_b32_e32 v0, v0, v61, vcc
	v_rsq_f32_e32 v0, v0
	s_nop 0
	v_mul_f32_e32 v61, 0x45800000, v0
	v_cndmask_b32_e32 v68, v0, v61, vcc
	v_subrev_u32_e32 v0, 64, v39
	v_lshlrev_b64 v[70:71], 13, v[0:1]
	v_lshl_add_u64 v[62:63], v[62:63], 0, v[70:71]
	v_mov_b32_e32 v61, v1
	v_pk_mul_f32 v[6:7], v[6:7], v[68:69] op_sel_hi:[1,0]
	v_pk_mul_f32 v[8:9], v[8:9], v[68:69] op_sel_hi:[1,0]
	v_lshl_add_u64 v[62:63], v[62:63], 0, v[60:61]
	s_waitcnt vmcnt(0)
	v_pk_mul_f32 v[6:7], v[64:65], v[6:7]
	v_pk_mul_f32 v[8:9], v[66:67], v[8:9]
	global_store_dwordx4 v[62:63], v[6:9], off
	s_nop 1
	v_mov_b32_e32 v6, v154
	v_mov_b32_e32 v7, v155
	v_mov_b32_e32 v8, v156
	v_mov_b32_e32 v9, v157
	v_pk_mul_f32 v[10:11], v[10:11], v[68:69] op_sel_hi:[1,0]
	v_pk_mul_f32 v[12:13], v[12:13], v[68:69] op_sel_hi:[1,0]
	v_pk_mul_f32 v[6:7], v[6:7], v[10:11]
	v_pk_mul_f32 v[8:9], v[8:9], v[12:13]
	global_store_dwordx4 v[62:63], v[6:9], off offset:1024
	s_nop 1
	v_mov_b32_e32 v6, v158
	v_mov_b32_e32 v7, v159
	v_mov_b32_e32 v8, v160
	v_mov_b32_e32 v9, v161
	v_pk_mul_f32 v[10:11], v[14:15], v[68:69] op_sel_hi:[1,0]
	v_pk_mul_f32 v[12:13], v[16:17], v[68:69] op_sel_hi:[1,0]
	v_pk_mul_f32 v[14:15], v[24:25], v[68:69] op_sel_hi:[1,0]
	v_pk_mul_f32 v[6:7], v[10:11], v[6:7]
	v_pk_mul_f32 v[8:9], v[12:13], v[8:9]
	global_store_dwordx4 v[62:63], v[6:9], off offset:2048
	s_nop 1
	v_mov_b32_e32 v6, v162
	v_mov_b32_e32 v7, v163
	v_mov_b32_e32 v8, v164
	v_mov_b32_e32 v9, v165
	v_pk_mul_f32 v[10:11], v[18:19], v[68:69] op_sel_hi:[1,0]
	v_pk_mul_f32 v[12:13], v[20:21], v[68:69] op_sel_hi:[1,0]
	v_pk_mul_f32 v[6:7], v[10:11], v[6:7]
	v_pk_mul_f32 v[8:9], v[12:13], v[8:9]
	global_store_dwordx4 v[62:63], v[6:9], off offset:3072
	s_nop 1
	v_mov_b32_e32 v6, v170
	v_mov_b32_e32 v7, v171
	v_mov_b32_e32 v8, v172
	v_mov_b32_e32 v9, v173
	v_add_co_u32_e32 v10, vcc, s1, v62
	v_pk_mul_f32 v[12:13], v[22:23], v[68:69] op_sel_hi:[1,0]
	s_nop 0
	v_addc_co_u32_e32 v11, vcc, 0, v63, vcc
	v_pk_mul_f32 v[6:7], v[12:13], v[6:7]
	v_pk_mul_f32 v[8:9], v[14:15], v[8:9]
	global_store_dwordx4 v[10:11], v[6:9], off
	s_nop 1
	v_mov_b32_e32 v6, v174
	v_mov_b32_e32 v7, v175
	v_mov_b32_e32 v8, v176
	v_mov_b32_e32 v9, v177
	v_pk_mul_f32 v[12:13], v[26:27], v[68:69] op_sel_hi:[1,0]
	v_pk_mul_f32 v[14:15], v[28:29], v[68:69] op_sel_hi:[1,0]
	v_pk_mul_f32 v[6:7], v[12:13], v[6:7]
	v_pk_mul_f32 v[8:9], v[14:15], v[8:9]
	global_store_dwordx4 v[10:11], v[6:9], off offset:1024
	s_nop 1
	v_mov_b32_e32 v6, v182
	v_mov_b32_e32 v7, v183
	v_mov_b32_e32 v8, v184
	v_mov_b32_e32 v9, v185
	v_pk_mul_f32 v[12:13], v[30:31], v[68:69] op_sel_hi:[1,0]
	v_pk_mul_f32 v[14:15], v[32:33], v[68:69] op_sel_hi:[1,0]
	v_pk_mul_f32 v[6:7], v[12:13], v[6:7]
	v_pk_mul_f32 v[8:9], v[14:15], v[8:9]
	global_store_dwordx4 v[10:11], v[6:9], off offset:2048
	s_nop 1
	v_mov_b32_e32 v6, v186
	v_mov_b32_e32 v7, v187
	v_mov_b32_e32 v8, v188
	v_mov_b32_e32 v9, v189
	v_pk_mul_f32 v[12:13], v[34:35], v[68:69] op_sel_hi:[1,0]
	v_pk_mul_f32 v[14:15], v[36:37], v[68:69] op_sel_hi:[1,0]
	v_pk_mul_f32 v[6:7], v[12:13], v[6:7]
	v_pk_mul_f32 v[8:9], v[14:15], v[8:9]
	global_store_dwordx4 v[10:11], v[6:9], off offset:3072

.LBB0_951:
	v_add_u32_e32 v0, 0xffffe000, v38
	s_movk_i32 s1, 0x1fff
	v_lshlrev_b64 v[64:65], 13, v[0:1]
	v_cmp_lt_i32_e64 s[42:43], s1, v38
	v_lshl_add_u64 v[22:23], v[40:41], 0, v[64:65]
	s_and_saveexec_b64 s[18:19], s[42:43]
	s_cbranch_execz .LBB0_953
	v_add_co_u32_e32 v140, vcc, 0x200000, v22
	s_nop 1
	v_addc_co_u32_e32 v141, vcc, 0, v23, vcc
	v_add_co_u32_e32 v142, vcc, 0x400000, v22
	s_nop 1
	v_addc_co_u32_e32 v143, vcc, 0, v23, vcc
	v_add_co_u32_e32 v144, vcc, 0x600000, v22
	s_nop 1
	v_addc_co_u32_e32 v145, vcc, 0, v23, vcc
	v_add_co_u32_e32 v146, vcc, 0x800000, v22
	s_nop 1
	v_addc_co_u32_e32 v147, vcc, 0, v23, vcc
	v_add_co_u32_e32 v148, vcc, 0xa00000, v22
	s_nop 1
	v_addc_co_u32_e32 v149, vcc, 0, v23, vcc
	v_add_co_u32_e32 v150, vcc, 0xc00000, v22
	s_nop 1
	v_addc_co_u32_e32 v151, vcc, 0, v23, vcc
	v_add_co_u32_e32 v152, vcc, 0xe00000, v22
	s_nop 1
	v_addc_co_u32_e32 v153, vcc, 0, v23, vcc
	global_load_dwordx4 v[214:217], v[22:23], off
	global_load_dwordx4 v[218:221], v[140:141], off
	global_load_dwordx4 v[222:225], v[142:143], off
	global_load_dwordx4 v[226:229], v[144:145], off
	global_load_dwordx4 v[230:233], v[146:147], off
	global_load_dwordx4 v[234:237], v[148:149], off
	global_load_dwordx4 v[238:241], v[150:151], off
	global_load_dwordx4 v[242:245], v[152:153], off
	s_waitcnt vmcnt(7)
	v_pk_add_f32 v[246:247], v[6:7], v[214:215]
	v_pk_add_f32 v[248:249], v[8:9], v[216:217]
	s_waitcnt vmcnt(6)
	v_pk_add_f32 v[246:247], v[246:247], v[218:219]
	v_pk_add_f32 v[248:249], v[248:249], v[220:221]
	s_waitcnt vmcnt(5)
	v_pk_add_f32 v[246:247], v[246:247], v[222:223]
	v_pk_add_f32 v[248:249], v[248:249], v[224:225]
	s_waitcnt vmcnt(4)
	v_pk_add_f32 v[246:247], v[246:247], v[226:227]
	v_pk_add_f32 v[248:249], v[248:249], v[228:229]
	s_waitcnt vmcnt(3)
	v_pk_add_f32 v[246:247], v[246:247], v[230:231]
	v_pk_add_f32 v[248:249], v[248:249], v[232:233]
	s_waitcnt vmcnt(2)
	v_pk_add_f32 v[246:247], v[246:247], v[234:235]
	v_pk_add_f32 v[248:249], v[248:249], v[236:237]
	s_waitcnt vmcnt(1)
	v_pk_add_f32 v[246:247], v[246:247], v[238:239]
	v_pk_add_f32 v[248:249], v[248:249], v[240:241]
	s_waitcnt vmcnt(0)
	v_pk_add_f32 v[246:247], v[246:247], v[242:243]
	v_pk_add_f32 v[248:249], v[248:249], v[244:245]
	v_mov_b32_e32 v6, v246
	v_mov_b32_e32 v7, v247
	v_mov_b32_e32 v8, v248
	v_mov_b32_e32 v9, v249

.LBB0_955:
	v_add_co_u32_e32 v140, vcc, 0x200000, v22
	s_nop 1
	v_addc_co_u32_e32 v141, vcc, 0, v23, vcc
	v_add_co_u32_e32 v142, vcc, 0x400000, v22
	s_nop 1
	v_addc_co_u32_e32 v143, vcc, 0, v23, vcc
	v_add_co_u32_e32 v144, vcc, 0x600000, v22
	s_nop 1
	v_addc_co_u32_e32 v145, vcc, 0, v23, vcc
	v_add_co_u32_e32 v146, vcc, 0x800000, v22
	s_nop 1
	v_addc_co_u32_e32 v147, vcc, 0, v23, vcc
	v_add_co_u32_e32 v148, vcc, 0xa00000, v22
	s_nop 1
	v_addc_co_u32_e32 v149, vcc, 0, v23, vcc
	v_add_co_u32_e32 v150, vcc, 0xc00000, v22
	s_nop 1
	v_addc_co_u32_e32 v151, vcc, 0, v23, vcc
	v_add_co_u32_e32 v152, vcc, 0xe00000, v22
	s_nop 1
	v_addc_co_u32_e32 v153, vcc, 0, v23, vcc
	global_load_dwordx4 v[214:217], v[22:23], off offset:1024
	global_load_dwordx4 v[218:221], v[140:141], off offset:1024
	global_load_dwordx4 v[222:225], v[142:143], off offset:1024
	global_load_dwordx4 v[226:229], v[144:145], off offset:1024
	global_load_dwordx4 v[230:233], v[146:147], off offset:1024
	global_load_dwordx4 v[234:237], v[148:149], off offset:1024
	global_load_dwordx4 v[238:241], v[150:151], off offset:1024
	global_load_dwordx4 v[242:245], v[152:153], off offset:1024
	s_waitcnt vmcnt(7)
	v_pk_add_f32 v[246:247], v[10:11], v[214:215]
	v_pk_add_f32 v[248:249], v[12:13], v[216:217]
	s_waitcnt vmcnt(6)
	v_pk_add_f32 v[246:247], v[246:247], v[218:219]
	v_pk_add_f32 v[248:249], v[248:249], v[220:221]
	s_waitcnt vmcnt(5)
	v_pk_add_f32 v[246:247], v[246:247], v[222:223]
	v_pk_add_f32 v[248:249], v[248:249], v[224:225]
	s_waitcnt vmcnt(4)
	v_pk_add_f32 v[246:247], v[246:247], v[226:227]
	v_pk_add_f32 v[248:249], v[248:249], v[228:229]
	s_waitcnt vmcnt(3)
	v_pk_add_f32 v[246:247], v[246:247], v[230:231]
	v_pk_add_f32 v[248:249], v[248:249], v[232:233]
	s_waitcnt vmcnt(2)
	v_pk_add_f32 v[246:247], v[246:247], v[234:235]
	v_pk_add_f32 v[248:249], v[248:249], v[236:237]
	s_waitcnt vmcnt(1)
	v_pk_add_f32 v[246:247], v[246:247], v[238:239]
	v_pk_add_f32 v[248:249], v[248:249], v[240:241]
	s_waitcnt vmcnt(0)
	v_pk_add_f32 v[246:247], v[246:247], v[242:243]
	v_pk_add_f32 v[248:249], v[248:249], v[244:245]
	v_mov_b32_e32 v10, v246
	v_mov_b32_e32 v11, v247
	v_mov_b32_e32 v12, v248
	v_mov_b32_e32 v13, v249

.LBB0_958:
	v_add_co_u32_e32 v140, vcc, 0x200000, v22
	s_nop 1
	v_addc_co_u32_e32 v141, vcc, 0, v23, vcc
	v_add_co_u32_e32 v142, vcc, 0x400000, v22
	s_nop 1
	v_addc_co_u32_e32 v143, vcc, 0, v23, vcc
	v_add_co_u32_e32 v144, vcc, 0x600000, v22
	s_nop 1
	v_addc_co_u32_e32 v145, vcc, 0, v23, vcc
	v_add_co_u32_e32 v146, vcc, 0x800000, v22
	s_nop 1
	v_addc_co_u32_e32 v147, vcc, 0, v23, vcc
	v_add_co_u32_e32 v148, vcc, 0xa00000, v22
	s_nop 1
	v_addc_co_u32_e32 v149, vcc, 0, v23, vcc
	v_add_co_u32_e32 v150, vcc, 0xc00000, v22
	s_nop 1
	v_addc_co_u32_e32 v151, vcc, 0, v23, vcc
	v_add_co_u32_e32 v152, vcc, 0xe00000, v22
	s_nop 1
	v_addc_co_u32_e32 v153, vcc, 0, v23, vcc
	global_load_dwordx4 v[214:217], v[22:23], off offset:2048
	global_load_dwordx4 v[218:221], v[140:141], off offset:2048
	global_load_dwordx4 v[222:225], v[142:143], off offset:2048
	global_load_dwordx4 v[226:229], v[144:145], off offset:2048
	global_load_dwordx4 v[230:233], v[146:147], off offset:2048
	global_load_dwordx4 v[234:237], v[148:149], off offset:2048
	global_load_dwordx4 v[238:241], v[150:151], off offset:2048
	global_load_dwordx4 v[242:245], v[152:153], off offset:2048
	s_waitcnt vmcnt(7)
	v_pk_add_f32 v[246:247], v[14:15], v[214:215]
	v_pk_add_f32 v[248:249], v[16:17], v[216:217]
	s_waitcnt vmcnt(6)
	v_pk_add_f32 v[246:247], v[246:247], v[218:219]
	v_pk_add_f32 v[248:249], v[248:249], v[220:221]
	s_waitcnt vmcnt(5)
	v_pk_add_f32 v[246:247], v[246:247], v[222:223]
	v_pk_add_f32 v[248:249], v[248:249], v[224:225]
	s_waitcnt vmcnt(4)
	v_pk_add_f32 v[246:247], v[246:247], v[226:227]
	v_pk_add_f32 v[248:249], v[248:249], v[228:229]
	s_waitcnt vmcnt(3)
	v_pk_add_f32 v[246:247], v[246:247], v[230:231]
	v_pk_add_f32 v[248:249], v[248:249], v[232:233]
	s_waitcnt vmcnt(2)
	v_pk_add_f32 v[246:247], v[246:247], v[234:235]
	v_pk_add_f32 v[248:249], v[248:249], v[236:237]
	s_waitcnt vmcnt(1)
	v_pk_add_f32 v[246:247], v[246:247], v[238:239]
	v_pk_add_f32 v[248:249], v[248:249], v[240:241]
	s_waitcnt vmcnt(0)
	v_pk_add_f32 v[246:247], v[246:247], v[242:243]
	v_pk_add_f32 v[248:249], v[248:249], v[244:245]
	v_mov_b32_e32 v14, v246
	v_mov_b32_e32 v15, v247
	v_mov_b32_e32 v16, v248
	v_mov_b32_e32 v17, v249

.LBB0_961:
	v_add_co_u32_e32 v140, vcc, 0x200000, v22
	s_nop 1
	v_addc_co_u32_e32 v141, vcc, 0, v23, vcc
	v_add_co_u32_e32 v142, vcc, 0x400000, v22
	s_nop 1
	v_addc_co_u32_e32 v143, vcc, 0, v23, vcc
	v_add_co_u32_e32 v144, vcc, 0x600000, v22
	s_nop 1
	v_addc_co_u32_e32 v145, vcc, 0, v23, vcc
	v_add_co_u32_e32 v146, vcc, 0x800000, v22
	s_nop 1
	v_addc_co_u32_e32 v147, vcc, 0, v23, vcc
	v_add_co_u32_e32 v148, vcc, 0xa00000, v22
	s_nop 1
	v_addc_co_u32_e32 v149, vcc, 0, v23, vcc
	v_add_co_u32_e32 v150, vcc, 0xc00000, v22
	s_nop 1
	v_addc_co_u32_e32 v151, vcc, 0, v23, vcc
	v_add_co_u32_e32 v152, vcc, 0xe00000, v22
	s_nop 1
	v_addc_co_u32_e32 v153, vcc, 0, v23, vcc
	global_load_dwordx4 v[214:217], v[22:23], off offset:3072
	global_load_dwordx4 v[218:221], v[140:141], off offset:3072
	global_load_dwordx4 v[222:225], v[142:143], off offset:3072
	global_load_dwordx4 v[226:229], v[144:145], off offset:3072
	global_load_dwordx4 v[230:233], v[146:147], off offset:3072
	global_load_dwordx4 v[234:237], v[148:149], off offset:3072
	global_load_dwordx4 v[238:241], v[150:151], off offset:3072
	global_load_dwordx4 v[242:245], v[152:153], off offset:3072
	s_waitcnt vmcnt(7)
	v_pk_add_f32 v[246:247], v[18:19], v[214:215]
	v_pk_add_f32 v[248:249], v[20:21], v[216:217]
	s_waitcnt vmcnt(6)
	v_pk_add_f32 v[246:247], v[246:247], v[218:219]
	v_pk_add_f32 v[248:249], v[248:249], v[220:221]
	s_waitcnt vmcnt(5)
	v_pk_add_f32 v[246:247], v[246:247], v[222:223]
	v_pk_add_f32 v[248:249], v[248:249], v[224:225]
	s_waitcnt vmcnt(4)
	v_pk_add_f32 v[246:247], v[246:247], v[226:227]
	v_pk_add_f32 v[248:249], v[248:249], v[228:229]
	s_waitcnt vmcnt(3)
	v_pk_add_f32 v[246:247], v[246:247], v[230:231]
	v_pk_add_f32 v[248:249], v[248:249], v[232:233]
	s_waitcnt vmcnt(2)
	v_pk_add_f32 v[246:247], v[246:247], v[234:235]
	v_pk_add_f32 v[248:249], v[248:249], v[236:237]
	s_waitcnt vmcnt(1)
	v_pk_add_f32 v[246:247], v[246:247], v[238:239]
	v_pk_add_f32 v[248:249], v[248:249], v[240:241]
	s_waitcnt vmcnt(0)
	v_pk_add_f32 v[246:247], v[246:247], v[242:243]
	v_pk_add_f32 v[248:249], v[248:249], v[244:245]
	v_mov_b32_e32 v18, v246
	v_mov_b32_e32 v19, v247
	v_mov_b32_e32 v20, v248
	v_mov_b32_e32 v21, v249

.LBB0_964:
	v_lshl_add_u64 v[74:75], v[42:43], 0, v[64:65]
	v_add_co_u32_e32 v140, vcc, 0x200000, v74
	s_nop 1
	v_addc_co_u32_e32 v141, vcc, 0, v75, vcc
	v_add_co_u32_e32 v142, vcc, 0x400000, v74
	s_nop 1
	v_addc_co_u32_e32 v143, vcc, 0, v75, vcc
	v_add_co_u32_e32 v144, vcc, 0x600000, v74
	s_nop 1
	v_addc_co_u32_e32 v145, vcc, 0, v75, vcc
	v_add_co_u32_e32 v146, vcc, 0x800000, v74
	s_nop 1
	v_addc_co_u32_e32 v147, vcc, 0, v75, vcc
	v_add_co_u32_e32 v148, vcc, 0xa00000, v74
	s_nop 1
	v_addc_co_u32_e32 v149, vcc, 0, v75, vcc
	v_add_co_u32_e32 v150, vcc, 0xc00000, v74
	s_nop 1
	v_addc_co_u32_e32 v151, vcc, 0, v75, vcc
	v_add_co_u32_e32 v152, vcc, 0xe00000, v74
	s_nop 1
	v_addc_co_u32_e32 v153, vcc, 0, v75, vcc
	global_load_dwordx4 v[214:217], v[74:75], off
	global_load_dwordx4 v[218:221], v[140:141], off
	global_load_dwordx4 v[222:225], v[142:143], off
	global_load_dwordx4 v[226:229], v[144:145], off
	global_load_dwordx4 v[230:233], v[146:147], off
	global_load_dwordx4 v[234:237], v[148:149], off
	global_load_dwordx4 v[238:241], v[150:151], off
	global_load_dwordx4 v[242:245], v[152:153], off
	s_waitcnt vmcnt(7)
	v_pk_add_f32 v[246:247], v[22:23], v[214:215]
	v_pk_add_f32 v[248:249], v[24:25], v[216:217]
	s_waitcnt vmcnt(6)
	v_pk_add_f32 v[246:247], v[246:247], v[218:219]
	v_pk_add_f32 v[248:249], v[248:249], v[220:221]
	s_waitcnt vmcnt(5)
	v_pk_add_f32 v[246:247], v[246:247], v[222:223]
	v_pk_add_f32 v[248:249], v[248:249], v[224:225]
	s_waitcnt vmcnt(4)
	v_pk_add_f32 v[246:247], v[246:247], v[226:227]
	v_pk_add_f32 v[248:249], v[248:249], v[228:229]
	s_waitcnt vmcnt(3)
	v_pk_add_f32 v[246:247], v[246:247], v[230:231]
	v_pk_add_f32 v[248:249], v[248:249], v[232:233]
	s_waitcnt vmcnt(2)
	v_pk_add_f32 v[246:247], v[246:247], v[234:235]
	v_pk_add_f32 v[248:249], v[248:249], v[236:237]
	s_waitcnt vmcnt(1)
	v_pk_add_f32 v[246:247], v[246:247], v[238:239]
	v_pk_add_f32 v[248:249], v[248:249], v[240:241]
	s_waitcnt vmcnt(0)
	v_pk_add_f32 v[246:247], v[246:247], v[242:243]
	v_pk_add_f32 v[248:249], v[248:249], v[244:245]
	v_mov_b32_e32 v22, v246
	v_mov_b32_e32 v23, v247
	v_mov_b32_e32 v24, v248
	v_mov_b32_e32 v25, v249

.LBB0_967:
	v_lshl_add_u64 v[78:79], v[44:45], 0, v[64:65]
	v_add_co_u32_e32 v140, vcc, 0x200000, v78
	s_nop 1
	v_addc_co_u32_e32 v141, vcc, 0, v79, vcc
	v_add_co_u32_e32 v142, vcc, 0x400000, v78
	s_nop 1
	v_addc_co_u32_e32 v143, vcc, 0, v79, vcc
	v_add_co_u32_e32 v144, vcc, 0x600000, v78
	s_nop 1
	v_addc_co_u32_e32 v145, vcc, 0, v79, vcc
	v_add_co_u32_e32 v146, vcc, 0x800000, v78
	s_nop 1
	v_addc_co_u32_e32 v147, vcc, 0, v79, vcc
	v_add_co_u32_e32 v148, vcc, 0xa00000, v78
	s_nop 1
	v_addc_co_u32_e32 v149, vcc, 0, v79, vcc
	v_add_co_u32_e32 v150, vcc, 0xc00000, v78
	s_nop 1
	v_addc_co_u32_e32 v151, vcc, 0, v79, vcc
	v_add_co_u32_e32 v152, vcc, 0xe00000, v78
	s_nop 1
	v_addc_co_u32_e32 v153, vcc, 0, v79, vcc
	global_load_dwordx4 v[214:217], v[78:79], off
	global_load_dwordx4 v[218:221], v[140:141], off
	global_load_dwordx4 v[222:225], v[142:143], off
	global_load_dwordx4 v[226:229], v[144:145], off
	global_load_dwordx4 v[230:233], v[146:147], off
	global_load_dwordx4 v[234:237], v[148:149], off
	global_load_dwordx4 v[238:241], v[150:151], off
	global_load_dwordx4 v[242:245], v[152:153], off
	s_waitcnt vmcnt(7)
	v_pk_add_f32 v[246:247], v[26:27], v[214:215]
	v_pk_add_f32 v[248:249], v[28:29], v[216:217]
	s_waitcnt vmcnt(6)
	v_pk_add_f32 v[246:247], v[246:247], v[218:219]
	v_pk_add_f32 v[248:249], v[248:249], v[220:221]
	s_waitcnt vmcnt(5)
	v_pk_add_f32 v[246:247], v[246:247], v[222:223]
	v_pk_add_f32 v[248:249], v[248:249], v[224:225]
	s_waitcnt vmcnt(4)
	v_pk_add_f32 v[246:247], v[246:247], v[226:227]
	v_pk_add_f32 v[248:249], v[248:249], v[228:229]
	s_waitcnt vmcnt(3)
	v_pk_add_f32 v[246:247], v[246:247], v[230:231]
	v_pk_add_f32 v[248:249], v[248:249], v[232:233]
	s_waitcnt vmcnt(2)
	v_pk_add_f32 v[246:247], v[246:247], v[234:235]
	v_pk_add_f32 v[248:249], v[248:249], v[236:237]
	s_waitcnt vmcnt(1)
	v_pk_add_f32 v[246:247], v[246:247], v[238:239]
	v_pk_add_f32 v[248:249], v[248:249], v[240:241]
	s_waitcnt vmcnt(0)
	v_pk_add_f32 v[246:247], v[246:247], v[242:243]
	v_pk_add_f32 v[248:249], v[248:249], v[244:245]
	v_mov_b32_e32 v26, v246
	v_mov_b32_e32 v27, v247
	v_mov_b32_e32 v28, v248
	v_mov_b32_e32 v29, v249

.LBB0_970:
	v_lshl_add_u64 v[82:83], v[46:47], 0, v[64:65]
	v_add_co_u32_e32 v140, vcc, 0x200000, v82
	s_nop 1
	v_addc_co_u32_e32 v141, vcc, 0, v83, vcc
	v_add_co_u32_e32 v142, vcc, 0x400000, v82
	s_nop 1
	v_addc_co_u32_e32 v143, vcc, 0, v83, vcc
	v_add_co_u32_e32 v144, vcc, 0x600000, v82
	s_nop 1
	v_addc_co_u32_e32 v145, vcc, 0, v83, vcc
	v_add_co_u32_e32 v146, vcc, 0x800000, v82
	s_nop 1
	v_addc_co_u32_e32 v147, vcc, 0, v83, vcc
	v_add_co_u32_e32 v148, vcc, 0xa00000, v82
	s_nop 1
	v_addc_co_u32_e32 v149, vcc, 0, v83, vcc
	v_add_co_u32_e32 v150, vcc, 0xc00000, v82
	s_nop 1
	v_addc_co_u32_e32 v151, vcc, 0, v83, vcc
	v_add_co_u32_e32 v152, vcc, 0xe00000, v82
	s_nop 1
	v_addc_co_u32_e32 v153, vcc, 0, v83, vcc
	global_load_dwordx4 v[214:217], v[82:83], off
	global_load_dwordx4 v[218:221], v[140:141], off
	global_load_dwordx4 v[222:225], v[142:143], off
	global_load_dwordx4 v[226:229], v[144:145], off
	global_load_dwordx4 v[230:233], v[146:147], off
	global_load_dwordx4 v[234:237], v[148:149], off
	global_load_dwordx4 v[238:241], v[150:151], off
	global_load_dwordx4 v[242:245], v[152:153], off
	s_waitcnt vmcnt(7)
	v_pk_add_f32 v[246:247], v[30:31], v[214:215]
	v_pk_add_f32 v[248:249], v[32:33], v[216:217]
	s_waitcnt vmcnt(6)
	v_pk_add_f32 v[246:247], v[246:247], v[218:219]
	v_pk_add_f32 v[248:249], v[248:249], v[220:221]
	s_waitcnt vmcnt(5)
	v_pk_add_f32 v[246:247], v[246:247], v[222:223]
	v_pk_add_f32 v[248:249], v[248:249], v[224:225]
	s_waitcnt vmcnt(4)
	v_pk_add_f32 v[246:247], v[246:247], v[226:227]
	v_pk_add_f32 v[248:249], v[248:249], v[228:229]
	s_waitcnt vmcnt(3)
	v_pk_add_f32 v[246:247], v[246:247], v[230:231]
	v_pk_add_f32 v[248:249], v[248:249], v[232:233]
	s_waitcnt vmcnt(2)
	v_pk_add_f32 v[246:247], v[246:247], v[234:235]
	v_pk_add_f32 v[248:249], v[248:249], v[236:237]
	s_waitcnt vmcnt(1)
	v_pk_add_f32 v[246:247], v[246:247], v[238:239]
	v_pk_add_f32 v[248:249], v[248:249], v[240:241]
	s_waitcnt vmcnt(0)
	v_pk_add_f32 v[246:247], v[246:247], v[242:243]
	v_pk_add_f32 v[248:249], v[248:249], v[244:245]
	v_mov_b32_e32 v30, v246
	v_mov_b32_e32 v31, v247
	v_mov_b32_e32 v32, v248
	v_mov_b32_e32 v33, v249

.LBB0_980:
	v_lshl_add_u64 v[84:85], v[48:49], 0, v[64:65]
	v_add_co_u32_e32 v140, vcc, 0x200000, v84
	s_nop 1
	v_addc_co_u32_e32 v141, vcc, 0, v85, vcc
	v_add_co_u32_e32 v142, vcc, 0x400000, v84
	s_nop 1
	v_addc_co_u32_e32 v143, vcc, 0, v85, vcc
	v_add_co_u32_e32 v144, vcc, 0x600000, v84
	s_nop 1
	v_addc_co_u32_e32 v145, vcc, 0, v85, vcc
	v_add_co_u32_e32 v146, vcc, 0x800000, v84
	s_nop 1
	v_addc_co_u32_e32 v147, vcc, 0, v85, vcc
	v_add_co_u32_e32 v148, vcc, 0xa00000, v84
	s_nop 1
	v_addc_co_u32_e32 v149, vcc, 0, v85, vcc
	v_add_co_u32_e32 v150, vcc, 0xc00000, v84
	s_nop 1
	v_addc_co_u32_e32 v151, vcc, 0, v85, vcc
	v_add_co_u32_e32 v152, vcc, 0xe00000, v84
	s_nop 1
	v_addc_co_u32_e32 v153, vcc, 0, v85, vcc
	global_load_dwordx4 v[214:217], v[84:85], off
	global_load_dwordx4 v[218:221], v[140:141], off
	global_load_dwordx4 v[222:225], v[142:143], off
	global_load_dwordx4 v[226:229], v[144:145], off
	global_load_dwordx4 v[230:233], v[146:147], off
	global_load_dwordx4 v[234:237], v[148:149], off
	global_load_dwordx4 v[238:241], v[150:151], off
	global_load_dwordx4 v[242:245], v[152:153], off
	s_waitcnt vmcnt(7)
	v_pk_add_f32 v[246:247], v[34:35], v[214:215]
	v_pk_add_f32 v[248:249], v[36:37], v[216:217]
	s_waitcnt vmcnt(6)
	v_pk_add_f32 v[246:247], v[246:247], v[218:219]
	v_pk_add_f32 v[248:249], v[248:249], v[220:221]
	s_waitcnt vmcnt(5)
	v_pk_add_f32 v[246:247], v[246:247], v[222:223]
	v_pk_add_f32 v[248:249], v[248:249], v[224:225]
	s_waitcnt vmcnt(4)
	v_pk_add_f32 v[246:247], v[246:247], v[226:227]
	v_pk_add_f32 v[248:249], v[248:249], v[228:229]
	s_waitcnt vmcnt(3)
	v_pk_add_f32 v[246:247], v[246:247], v[230:231]
	v_pk_add_f32 v[248:249], v[248:249], v[232:233]
	s_waitcnt vmcnt(2)
	v_pk_add_f32 v[246:247], v[246:247], v[234:235]
	v_pk_add_f32 v[248:249], v[248:249], v[236:237]
	s_waitcnt vmcnt(1)
	v_pk_add_f32 v[246:247], v[246:247], v[238:239]
	v_pk_add_f32 v[248:249], v[248:249], v[240:241]
	s_waitcnt vmcnt(0)
	v_pk_add_f32 v[246:247], v[246:247], v[242:243]
	v_pk_add_f32 v[248:249], v[248:249], v[244:245]
	v_mov_b32_e32 v34, v246
	v_mov_b32_e32 v35, v247
	v_mov_b32_e32 v36, v248
	v_mov_b32_e32 v37, v249
	s_branch .LBB0_945

.LBB0_994:
	s_or_b64 exec, exec, s[18:19]
	v_add_u32_e32 v10, 0xffffe000, v38
	v_mov_b32_e32 v11, v1
	s_movk_i32 s1, 0x1fff
	v_lshlrev_b64 v[58:59], 13, v[10:11]
	v_cmp_lt_i32_e64 s[42:43], s1, v38
	v_lshl_add_u64 v[22:23], v[40:41], 0, v[58:59]
	s_and_saveexec_b64 s[18:19], s[42:43]
	s_cbranch_execz .LBB0_996
	v_add_co_u32_e32 v140, vcc, 0x200000, v22
	s_nop 1
	v_addc_co_u32_e32 v141, vcc, 0, v23, vcc
	v_add_co_u32_e32 v142, vcc, 0x400000, v22
	s_nop 1
	v_addc_co_u32_e32 v143, vcc, 0, v23, vcc
	v_add_co_u32_e32 v144, vcc, 0x600000, v22
	s_nop 1
	v_addc_co_u32_e32 v145, vcc, 0, v23, vcc
	v_add_co_u32_e32 v146, vcc, 0x800000, v22
	s_nop 1
	v_addc_co_u32_e32 v147, vcc, 0, v23, vcc
	v_add_co_u32_e32 v148, vcc, 0xa00000, v22
	s_nop 1
	v_addc_co_u32_e32 v149, vcc, 0, v23, vcc
	v_add_co_u32_e32 v150, vcc, 0xc00000, v22
	s_nop 1
	v_addc_co_u32_e32 v151, vcc, 0, v23, vcc
	v_add_co_u32_e32 v152, vcc, 0xe00000, v22
	s_nop 1
	v_addc_co_u32_e32 v153, vcc, 0, v23, vcc
	global_load_dwordx4 v[214:217], v[22:23], off
	global_load_dwordx4 v[218:221], v[140:141], off
	global_load_dwordx4 v[222:225], v[142:143], off
	global_load_dwordx4 v[226:229], v[144:145], off
	global_load_dwordx4 v[230:233], v[146:147], off
	global_load_dwordx4 v[234:237], v[148:149], off
	global_load_dwordx4 v[238:241], v[150:151], off
	global_load_dwordx4 v[242:245], v[152:153], off
	s_waitcnt vmcnt(7)
	v_pk_add_f32 v[246:247], v[6:7], v[214:215]
	v_pk_add_f32 v[248:249], v[8:9], v[216:217]
	s_waitcnt vmcnt(6)
	v_pk_add_f32 v[246:247], v[246:247], v[218:219]
	v_pk_add_f32 v[248:249], v[248:249], v[220:221]
	s_waitcnt vmcnt(5)
	v_pk_add_f32 v[246:247], v[246:247], v[222:223]
	v_pk_add_f32 v[248:249], v[248:249], v[224:225]
	s_waitcnt vmcnt(4)
	v_pk_add_f32 v[246:247], v[246:247], v[226:227]
	v_pk_add_f32 v[248:249], v[248:249], v[228:229]
	s_waitcnt vmcnt(3)
	v_pk_add_f32 v[246:247], v[246:247], v[230:231]
	v_pk_add_f32 v[248:249], v[248:249], v[232:233]
	s_waitcnt vmcnt(2)
	v_pk_add_f32 v[246:247], v[246:247], v[234:235]
	v_pk_add_f32 v[248:249], v[248:249], v[236:237]
	s_waitcnt vmcnt(1)
	v_pk_add_f32 v[246:247], v[246:247], v[238:239]
	v_pk_add_f32 v[248:249], v[248:249], v[240:241]
	s_waitcnt vmcnt(0)
	v_pk_add_f32 v[246:247], v[246:247], v[242:243]
	v_pk_add_f32 v[248:249], v[248:249], v[244:245]
	v_mov_b32_e32 v6, v246
	v_mov_b32_e32 v7, v247
	v_mov_b32_e32 v8, v248
	v_mov_b32_e32 v9, v249

.LBB0_998:
	s_or_b64 exec, exec, s[18:19]
	s_and_saveexec_b64 s[18:19], s[42:43]
	s_cbranch_execz .LBB0_1000
	v_add_co_u32_e32 v140, vcc, 0x200000, v22
	s_nop 1
	v_addc_co_u32_e32 v141, vcc, 0, v23, vcc
	v_add_co_u32_e32 v142, vcc, 0x400000, v22
	s_nop 1
	v_addc_co_u32_e32 v143, vcc, 0, v23, vcc
	v_add_co_u32_e32 v144, vcc, 0x600000, v22
	s_nop 1
	v_addc_co_u32_e32 v145, vcc, 0, v23, vcc
	v_add_co_u32_e32 v146, vcc, 0x800000, v22
	s_nop 1
	v_addc_co_u32_e32 v147, vcc, 0, v23, vcc
	v_add_co_u32_e32 v148, vcc, 0xa00000, v22
	s_nop 1
	v_addc_co_u32_e32 v149, vcc, 0, v23, vcc
	v_add_co_u32_e32 v150, vcc, 0xc00000, v22
	s_nop 1
	v_addc_co_u32_e32 v151, vcc, 0, v23, vcc
	v_add_co_u32_e32 v152, vcc, 0xe00000, v22
	s_nop 1
	v_addc_co_u32_e32 v153, vcc, 0, v23, vcc
	global_load_dwordx4 v[214:217], v[22:23], off offset:1024
	global_load_dwordx4 v[218:221], v[140:141], off offset:1024
	global_load_dwordx4 v[222:225], v[142:143], off offset:1024
	global_load_dwordx4 v[226:229], v[144:145], off offset:1024
	global_load_dwordx4 v[230:233], v[146:147], off offset:1024
	global_load_dwordx4 v[234:237], v[148:149], off offset:1024
	global_load_dwordx4 v[238:241], v[150:151], off offset:1024
	global_load_dwordx4 v[242:245], v[152:153], off offset:1024
	s_waitcnt vmcnt(7)
	v_pk_add_f32 v[246:247], v[10:11], v[214:215]
	v_pk_add_f32 v[248:249], v[12:13], v[216:217]
	s_waitcnt vmcnt(6)
	v_pk_add_f32 v[246:247], v[246:247], v[218:219]
	v_pk_add_f32 v[248:249], v[248:249], v[220:221]
	s_waitcnt vmcnt(5)
	v_pk_add_f32 v[246:247], v[246:247], v[222:223]
	v_pk_add_f32 v[248:249], v[248:249], v[224:225]
	s_waitcnt vmcnt(4)
	v_pk_add_f32 v[246:247], v[246:247], v[226:227]
	v_pk_add_f32 v[248:249], v[248:249], v[228:229]
	s_waitcnt vmcnt(3)
	v_pk_add_f32 v[246:247], v[246:247], v[230:231]
	v_pk_add_f32 v[248:249], v[248:249], v[232:233]
	s_waitcnt vmcnt(2)
	v_pk_add_f32 v[246:247], v[246:247], v[234:235]
	v_pk_add_f32 v[248:249], v[248:249], v[236:237]
	s_waitcnt vmcnt(1)
	v_pk_add_f32 v[246:247], v[246:247], v[238:239]
	v_pk_add_f32 v[248:249], v[248:249], v[240:241]
	s_waitcnt vmcnt(0)
	v_pk_add_f32 v[246:247], v[246:247], v[242:243]
	v_pk_add_f32 v[248:249], v[248:249], v[244:245]
	v_mov_b32_e32 v10, v246
	v_mov_b32_e32 v11, v247
	v_mov_b32_e32 v12, v248
	v_mov_b32_e32 v13, v249

.LBB0_1002:
	s_or_b64 exec, exec, s[18:19]
	s_and_saveexec_b64 s[18:19], s[42:43]
	s_cbranch_execz .LBB0_1004
	v_add_co_u32_e32 v140, vcc, 0x200000, v22
	s_nop 1
	v_addc_co_u32_e32 v141, vcc, 0, v23, vcc
	v_add_co_u32_e32 v142, vcc, 0x400000, v22
	s_nop 1
	v_addc_co_u32_e32 v143, vcc, 0, v23, vcc
	v_add_co_u32_e32 v144, vcc, 0x600000, v22
	s_nop 1
	v_addc_co_u32_e32 v145, vcc, 0, v23, vcc
	v_add_co_u32_e32 v146, vcc, 0x800000, v22
	s_nop 1
	v_addc_co_u32_e32 v147, vcc, 0, v23, vcc
	v_add_co_u32_e32 v148, vcc, 0xa00000, v22
	s_nop 1
	v_addc_co_u32_e32 v149, vcc, 0, v23, vcc
	v_add_co_u32_e32 v150, vcc, 0xc00000, v22
	s_nop 1
	v_addc_co_u32_e32 v151, vcc, 0, v23, vcc
	v_add_co_u32_e32 v152, vcc, 0xe00000, v22
	s_nop 1
	v_addc_co_u32_e32 v153, vcc, 0, v23, vcc
	global_load_dwordx4 v[214:217], v[22:23], off offset:2048
	global_load_dwordx4 v[218:221], v[140:141], off offset:2048
	global_load_dwordx4 v[222:225], v[142:143], off offset:2048
	global_load_dwordx4 v[226:229], v[144:145], off offset:2048
	global_load_dwordx4 v[230:233], v[146:147], off offset:2048
	global_load_dwordx4 v[234:237], v[148:149], off offset:2048
	global_load_dwordx4 v[238:241], v[150:151], off offset:2048
	global_load_dwordx4 v[242:245], v[152:153], off offset:2048
	s_waitcnt vmcnt(7)
	v_pk_add_f32 v[246:247], v[14:15], v[214:215]
	v_pk_add_f32 v[248:249], v[16:17], v[216:217]
	s_waitcnt vmcnt(6)
	v_pk_add_f32 v[246:247], v[246:247], v[218:219]
	v_pk_add_f32 v[248:249], v[248:249], v[220:221]
	s_waitcnt vmcnt(5)
	v_pk_add_f32 v[246:247], v[246:247], v[222:223]
	v_pk_add_f32 v[248:249], v[248:249], v[224:225]
	s_waitcnt vmcnt(4)
	v_pk_add_f32 v[246:247], v[246:247], v[226:227]
	v_pk_add_f32 v[248:249], v[248:249], v[228:229]
	s_waitcnt vmcnt(3)
	v_pk_add_f32 v[246:247], v[246:247], v[230:231]
	v_pk_add_f32 v[248:249], v[248:249], v[232:233]
	s_waitcnt vmcnt(2)
	v_pk_add_f32 v[246:247], v[246:247], v[234:235]
	v_pk_add_f32 v[248:249], v[248:249], v[236:237]
	s_waitcnt vmcnt(1)
	v_pk_add_f32 v[246:247], v[246:247], v[238:239]
	v_pk_add_f32 v[248:249], v[248:249], v[240:241]
	s_waitcnt vmcnt(0)
	v_pk_add_f32 v[246:247], v[246:247], v[242:243]
	v_pk_add_f32 v[248:249], v[248:249], v[244:245]
	v_mov_b32_e32 v14, v246
	v_mov_b32_e32 v15, v247
	v_mov_b32_e32 v16, v248
	v_mov_b32_e32 v17, v249

.LBB0_1006:
	s_or_b64 exec, exec, s[18:19]
	s_and_saveexec_b64 s[18:19], s[42:43]
	s_cbranch_execz .LBB0_1008
	v_add_co_u32_e32 v140, vcc, 0x200000, v22
	s_nop 1
	v_addc_co_u32_e32 v141, vcc, 0, v23, vcc
	v_add_co_u32_e32 v142, vcc, 0x400000, v22
	s_nop 1
	v_addc_co_u32_e32 v143, vcc, 0, v23, vcc
	v_add_co_u32_e32 v144, vcc, 0x600000, v22
	s_nop 1
	v_addc_co_u32_e32 v145, vcc, 0, v23, vcc
	v_add_co_u32_e32 v146, vcc, 0x800000, v22
	s_nop 1
	v_addc_co_u32_e32 v147, vcc, 0, v23, vcc
	v_add_co_u32_e32 v148, vcc, 0xa00000, v22
	s_nop 1
	v_addc_co_u32_e32 v149, vcc, 0, v23, vcc
	v_add_co_u32_e32 v150, vcc, 0xc00000, v22
	s_nop 1
	v_addc_co_u32_e32 v151, vcc, 0, v23, vcc
	v_add_co_u32_e32 v152, vcc, 0xe00000, v22
	s_nop 1
	v_addc_co_u32_e32 v153, vcc, 0, v23, vcc
	global_load_dwordx4 v[214:217], v[22:23], off offset:3072
	global_load_dwordx4 v[218:221], v[140:141], off offset:3072
	global_load_dwordx4 v[222:225], v[142:143], off offset:3072
	global_load_dwordx4 v[226:229], v[144:145], off offset:3072
	global_load_dwordx4 v[230:233], v[146:147], off offset:3072
	global_load_dwordx4 v[234:237], v[148:149], off offset:3072
	global_load_dwordx4 v[238:241], v[150:151], off offset:3072
	global_load_dwordx4 v[242:245], v[152:153], off offset:3072
	s_waitcnt vmcnt(7)
	v_pk_add_f32 v[246:247], v[18:19], v[214:215]
	v_pk_add_f32 v[248:249], v[20:21], v[216:217]
	s_waitcnt vmcnt(6)
	v_pk_add_f32 v[246:247], v[246:247], v[218:219]
	v_pk_add_f32 v[248:249], v[248:249], v[220:221]
	s_waitcnt vmcnt(5)
	v_pk_add_f32 v[246:247], v[246:247], v[222:223]
	v_pk_add_f32 v[248:249], v[248:249], v[224:225]
	s_waitcnt vmcnt(4)
	v_pk_add_f32 v[246:247], v[246:247], v[226:227]
	v_pk_add_f32 v[248:249], v[248:249], v[228:229]
	s_waitcnt vmcnt(3)
	v_pk_add_f32 v[246:247], v[246:247], v[230:231]
	v_pk_add_f32 v[248:249], v[248:249], v[232:233]
	s_waitcnt vmcnt(2)
	v_pk_add_f32 v[246:247], v[246:247], v[234:235]
	v_pk_add_f32 v[248:249], v[248:249], v[236:237]
	s_waitcnt vmcnt(1)
	v_pk_add_f32 v[246:247], v[246:247], v[238:239]
	v_pk_add_f32 v[248:249], v[248:249], v[240:241]
	s_waitcnt vmcnt(0)
	v_pk_add_f32 v[246:247], v[246:247], v[242:243]
	v_pk_add_f32 v[248:249], v[248:249], v[244:245]
	v_mov_b32_e32 v18, v246
	v_mov_b32_e32 v19, v247
	v_mov_b32_e32 v20, v248
	v_mov_b32_e32 v21, v249

.LBB0_1010:
	s_or_b64 exec, exec, s[18:19]
	s_and_saveexec_b64 s[18:19], s[42:43]
	s_cbranch_execz .LBB0_1012
	v_lshl_add_u64 v[82:83], v[42:43], 0, v[58:59]
	v_add_co_u32_e32 v140, vcc, 0x200000, v82
	s_nop 1
	v_addc_co_u32_e32 v141, vcc, 0, v83, vcc
	v_add_co_u32_e32 v142, vcc, 0x400000, v82
	s_nop 1
	v_addc_co_u32_e32 v143, vcc, 0, v83, vcc
	v_add_co_u32_e32 v144, vcc, 0x600000, v82
	s_nop 1
	v_addc_co_u32_e32 v145, vcc, 0, v83, vcc
	v_add_co_u32_e32 v146, vcc, 0x800000, v82
	s_nop 1
	v_addc_co_u32_e32 v147, vcc, 0, v83, vcc
	v_add_co_u32_e32 v148, vcc, 0xa00000, v82
	s_nop 1
	v_addc_co_u32_e32 v149, vcc, 0, v83, vcc
	v_add_co_u32_e32 v150, vcc, 0xc00000, v82
	s_nop 1
	v_addc_co_u32_e32 v151, vcc, 0, v83, vcc
	v_add_co_u32_e32 v152, vcc, 0xe00000, v82
	s_nop 1
	v_addc_co_u32_e32 v153, vcc, 0, v83, vcc
	global_load_dwordx4 v[214:217], v[82:83], off
	global_load_dwordx4 v[218:221], v[140:141], off
	global_load_dwordx4 v[222:225], v[142:143], off
	global_load_dwordx4 v[226:229], v[144:145], off
	global_load_dwordx4 v[230:233], v[146:147], off
	global_load_dwordx4 v[234:237], v[148:149], off
	global_load_dwordx4 v[238:241], v[150:151], off
	global_load_dwordx4 v[242:245], v[152:153], off
	s_waitcnt vmcnt(7)
	v_pk_add_f32 v[246:247], v[22:23], v[214:215]
	v_pk_add_f32 v[248:249], v[24:25], v[216:217]
	s_waitcnt vmcnt(6)
	v_pk_add_f32 v[246:247], v[246:247], v[218:219]
	v_pk_add_f32 v[248:249], v[248:249], v[220:221]
	s_waitcnt vmcnt(5)
	v_pk_add_f32 v[246:247], v[246:247], v[222:223]
	v_pk_add_f32 v[248:249], v[248:249], v[224:225]
	s_waitcnt vmcnt(4)
	v_pk_add_f32 v[246:247], v[246:247], v[226:227]
	v_pk_add_f32 v[248:249], v[248:249], v[228:229]
	s_waitcnt vmcnt(3)
	v_pk_add_f32 v[246:247], v[246:247], v[230:231]
	v_pk_add_f32 v[248:249], v[248:249], v[232:233]
	s_waitcnt vmcnt(2)
	v_pk_add_f32 v[246:247], v[246:247], v[234:235]
	v_pk_add_f32 v[248:249], v[248:249], v[236:237]
	s_waitcnt vmcnt(1)
	v_pk_add_f32 v[246:247], v[246:247], v[238:239]
	v_pk_add_f32 v[248:249], v[248:249], v[240:241]
	s_waitcnt vmcnt(0)
	v_pk_add_f32 v[246:247], v[246:247], v[242:243]
	v_pk_add_f32 v[248:249], v[248:249], v[244:245]
	v_mov_b32_e32 v22, v246
	v_mov_b32_e32 v23, v247
	v_mov_b32_e32 v24, v248
	v_mov_b32_e32 v25, v249

.LBB0_1014:
	s_or_b64 exec, exec, s[18:19]
	s_and_saveexec_b64 s[18:19], s[42:43]
	s_cbranch_execz .LBB0_1016
	v_lshl_add_u64 v[86:87], v[44:45], 0, v[58:59]
	v_add_co_u32_e32 v140, vcc, 0x200000, v86
	s_nop 1
	v_addc_co_u32_e32 v141, vcc, 0, v87, vcc
	v_add_co_u32_e32 v142, vcc, 0x400000, v86
	s_nop 1
	v_addc_co_u32_e32 v143, vcc, 0, v87, vcc
	v_add_co_u32_e32 v144, vcc, 0x600000, v86
	s_nop 1
	v_addc_co_u32_e32 v145, vcc, 0, v87, vcc
	v_add_co_u32_e32 v146, vcc, 0x800000, v86
	s_nop 1
	v_addc_co_u32_e32 v147, vcc, 0, v87, vcc
	v_add_co_u32_e32 v148, vcc, 0xa00000, v86
	s_nop 1
	v_addc_co_u32_e32 v149, vcc, 0, v87, vcc
	v_add_co_u32_e32 v150, vcc, 0xc00000, v86
	s_nop 1
	v_addc_co_u32_e32 v151, vcc, 0, v87, vcc
	v_add_co_u32_e32 v152, vcc, 0xe00000, v86
	s_nop 1
	v_addc_co_u32_e32 v153, vcc, 0, v87, vcc
	global_load_dwordx4 v[214:217], v[86:87], off
	global_load_dwordx4 v[218:221], v[140:141], off
	global_load_dwordx4 v[222:225], v[142:143], off
	global_load_dwordx4 v[226:229], v[144:145], off
	global_load_dwordx4 v[230:233], v[146:147], off
	global_load_dwordx4 v[234:237], v[148:149], off
	global_load_dwordx4 v[238:241], v[150:151], off
	global_load_dwordx4 v[242:245], v[152:153], off
	s_waitcnt vmcnt(7)
	v_pk_add_f32 v[246:247], v[26:27], v[214:215]
	v_pk_add_f32 v[248:249], v[28:29], v[216:217]
	s_waitcnt vmcnt(6)
	v_pk_add_f32 v[246:247], v[246:247], v[218:219]
	v_pk_add_f32 v[248:249], v[248:249], v[220:221]
	s_waitcnt vmcnt(5)
	v_pk_add_f32 v[246:247], v[246:247], v[222:223]
	v_pk_add_f32 v[248:249], v[248:249], v[224:225]
	s_waitcnt vmcnt(4)
	v_pk_add_f32 v[246:247], v[246:247], v[226:227]
	v_pk_add_f32 v[248:249], v[248:249], v[228:229]
	s_waitcnt vmcnt(3)
	v_pk_add_f32 v[246:247], v[246:247], v[230:231]
	v_pk_add_f32 v[248:249], v[248:249], v[232:233]
	s_waitcnt vmcnt(2)
	v_pk_add_f32 v[246:247], v[246:247], v[234:235]
	v_pk_add_f32 v[248:249], v[248:249], v[236:237]
	s_waitcnt vmcnt(1)
	v_pk_add_f32 v[246:247], v[246:247], v[238:239]
	v_pk_add_f32 v[248:249], v[248:249], v[240:241]
	s_waitcnt vmcnt(0)
	v_pk_add_f32 v[246:247], v[246:247], v[242:243]
	v_pk_add_f32 v[248:249], v[248:249], v[244:245]
	v_mov_b32_e32 v26, v246
	v_mov_b32_e32 v27, v247
	v_mov_b32_e32 v28, v248
	v_mov_b32_e32 v29, v249

.LBB0_1018:
	s_or_b64 exec, exec, s[18:19]
	s_and_saveexec_b64 s[18:19], s[42:43]
	s_cbranch_execz .LBB0_1020
	v_lshl_add_u64 v[90:91], v[46:47], 0, v[58:59]
	v_add_co_u32_e32 v140, vcc, 0x200000, v90
	s_nop 1
	v_addc_co_u32_e32 v141, vcc, 0, v91, vcc
	v_add_co_u32_e32 v142, vcc, 0x400000, v90
	s_nop 1
	v_addc_co_u32_e32 v143, vcc, 0, v91, vcc
	v_add_co_u32_e32 v144, vcc, 0x600000, v90
	s_nop 1
	v_addc_co_u32_e32 v145, vcc, 0, v91, vcc
	v_add_co_u32_e32 v146, vcc, 0x800000, v90
	s_nop 1
	v_addc_co_u32_e32 v147, vcc, 0, v91, vcc
	v_add_co_u32_e32 v148, vcc, 0xa00000, v90
	s_nop 1
	v_addc_co_u32_e32 v149, vcc, 0, v91, vcc
	v_add_co_u32_e32 v150, vcc, 0xc00000, v90
	s_nop 1
	v_addc_co_u32_e32 v151, vcc, 0, v91, vcc
	v_add_co_u32_e32 v152, vcc, 0xe00000, v90
	s_nop 1
	v_addc_co_u32_e32 v153, vcc, 0, v91, vcc
	global_load_dwordx4 v[214:217], v[90:91], off
	global_load_dwordx4 v[218:221], v[140:141], off
	global_load_dwordx4 v[222:225], v[142:143], off
	global_load_dwordx4 v[226:229], v[144:145], off
	global_load_dwordx4 v[230:233], v[146:147], off
	global_load_dwordx4 v[234:237], v[148:149], off
	global_load_dwordx4 v[238:241], v[150:151], off
	global_load_dwordx4 v[242:245], v[152:153], off
	s_waitcnt vmcnt(7)
	v_pk_add_f32 v[246:247], v[30:31], v[214:215]
	v_pk_add_f32 v[248:249], v[32:33], v[216:217]
	s_waitcnt vmcnt(6)
	v_pk_add_f32 v[246:247], v[246:247], v[218:219]
	v_pk_add_f32 v[248:249], v[248:249], v[220:221]
	s_waitcnt vmcnt(5)
	v_pk_add_f32 v[246:247], v[246:247], v[222:223]
	v_pk_add_f32 v[248:249], v[248:249], v[224:225]
	s_waitcnt vmcnt(4)
	v_pk_add_f32 v[246:247], v[246:247], v[226:227]
	v_pk_add_f32 v[248:249], v[248:249], v[228:229]
	s_waitcnt vmcnt(3)
	v_pk_add_f32 v[246:247], v[246:247], v[230:231]
	v_pk_add_f32 v[248:249], v[248:249], v[232:233]
	s_waitcnt vmcnt(2)
	v_pk_add_f32 v[246:247], v[246:247], v[234:235]
	v_pk_add_f32 v[248:249], v[248:249], v[236:237]
	s_waitcnt vmcnt(1)
	v_pk_add_f32 v[246:247], v[246:247], v[238:239]
	v_pk_add_f32 v[248:249], v[248:249], v[240:241]
	s_waitcnt vmcnt(0)
	v_pk_add_f32 v[246:247], v[246:247], v[242:243]
	v_pk_add_f32 v[248:249], v[248:249], v[244:245]
	v_mov_b32_e32 v30, v246
	v_mov_b32_e32 v31, v247
	v_mov_b32_e32 v32, v248
	v_mov_b32_e32 v33, v249

.LBB0_1022:
	s_or_b64 exec, exec, s[18:19]
	s_and_saveexec_b64 s[18:19], s[42:43]
	s_cbranch_execz .LBB0_1024
	v_lshl_add_u64 v[90:91], v[48:49], 0, v[58:59]
	v_add_co_u32_e32 v140, vcc, 0x200000, v90
	s_nop 1
	v_addc_co_u32_e32 v141, vcc, 0, v91, vcc
	v_add_co_u32_e32 v142, vcc, 0x400000, v90
	s_nop 1
	v_addc_co_u32_e32 v143, vcc, 0, v91, vcc
	v_add_co_u32_e32 v144, vcc, 0x600000, v90
	s_nop 1
	v_addc_co_u32_e32 v145, vcc, 0, v91, vcc
	v_add_co_u32_e32 v146, vcc, 0x800000, v90
	s_nop 1
	v_addc_co_u32_e32 v147, vcc, 0, v91, vcc
	v_add_co_u32_e32 v148, vcc, 0xa00000, v90
	s_nop 1
	v_addc_co_u32_e32 v149, vcc, 0, v91, vcc
	v_add_co_u32_e32 v150, vcc, 0xc00000, v90
	s_nop 1
	v_addc_co_u32_e32 v151, vcc, 0, v91, vcc
	v_add_co_u32_e32 v152, vcc, 0xe00000, v90
	s_nop 1
	v_addc_co_u32_e32 v153, vcc, 0, v91, vcc
	global_load_dwordx4 v[214:217], v[90:91], off
	global_load_dwordx4 v[218:221], v[140:141], off
	global_load_dwordx4 v[222:225], v[142:143], off
	global_load_dwordx4 v[226:229], v[144:145], off
	global_load_dwordx4 v[230:233], v[146:147], off
	global_load_dwordx4 v[234:237], v[148:149], off
	global_load_dwordx4 v[238:241], v[150:151], off
	global_load_dwordx4 v[242:245], v[152:153], off
	s_waitcnt vmcnt(7)
	v_pk_add_f32 v[246:247], v[34:35], v[214:215]
	v_pk_add_f32 v[248:249], v[36:37], v[216:217]
	s_waitcnt vmcnt(6)
	v_pk_add_f32 v[246:247], v[246:247], v[218:219]
	v_pk_add_f32 v[248:249], v[248:249], v[220:221]
	s_waitcnt vmcnt(5)
	v_pk_add_f32 v[246:247], v[246:247], v[222:223]
	v_pk_add_f32 v[248:249], v[248:249], v[224:225]
	s_waitcnt vmcnt(4)
	v_pk_add_f32 v[246:247], v[246:247], v[226:227]
	v_pk_add_f32 v[248:249], v[248:249], v[228:229]
	s_waitcnt vmcnt(3)
	v_pk_add_f32 v[246:247], v[246:247], v[230:231]
	v_pk_add_f32 v[248:249], v[248:249], v[232:233]
	s_waitcnt vmcnt(2)
	v_pk_add_f32 v[246:247], v[246:247], v[234:235]
	v_pk_add_f32 v[248:249], v[248:249], v[236:237]
	s_waitcnt vmcnt(1)
	v_pk_add_f32 v[246:247], v[246:247], v[238:239]
	v_pk_add_f32 v[248:249], v[248:249], v[240:241]
	s_waitcnt vmcnt(0)
	v_pk_add_f32 v[246:247], v[246:247], v[242:243]
	v_pk_add_f32 v[248:249], v[248:249], v[244:245]
	v_mov_b32_e32 v34, v246
	v_mov_b32_e32 v35, v247
	v_mov_b32_e32 v36, v248
	v_mov_b32_e32 v37, v249
